# attention main loops: drop the always-zero (mref - MOFF) term from the softmax check
# baseline (speedup 1.0000x reference)
.Lat1_apply:
	v_mov_b32_e32 v34, v84
	v_pk_add_f32 v[50:51], v[50:51], v[34:35] op_sel_hi:[1,0] neg_lo:[0,1] neg_hi:[0,1]
	v_pk_add_f32 v[66:67], v[66:67], v[34:35] op_sel_hi:[1,0] neg_lo:[0,1] neg_hi:[0,1]
	v_pk_add_f32 v[52:53], v[52:53], v[34:35] op_sel_hi:[1,0] neg_lo:[0,1] neg_hi:[0,1]
	v_pk_add_f32 v[68:69], v[68:69], v[34:35] op_sel_hi:[1,0] neg_lo:[0,1] neg_hi:[0,1]
	v_pk_add_f32 v[54:55], v[54:55], v[34:35] op_sel_hi:[1,0] neg_lo:[0,1] neg_hi:[0,1]
	v_pk_add_f32 v[70:71], v[70:71], v[34:35] op_sel_hi:[1,0] neg_lo:[0,1] neg_hi:[0,1]
	v_pk_add_f32 v[56:57], v[56:57], v[34:35] op_sel_hi:[1,0] neg_lo:[0,1] neg_hi:[0,1]
	v_pk_add_f32 v[72:73], v[72:73], v[34:35] op_sel_hi:[1,0] neg_lo:[0,1] neg_hi:[0,1]
	v_pk_add_f32 v[58:59], v[58:59], v[34:35] op_sel_hi:[1,0] neg_lo:[0,1] neg_hi:[0,1]
	v_pk_add_f32 v[74:75], v[74:75], v[34:35] op_sel_hi:[1,0] neg_lo:[0,1] neg_hi:[0,1]
	v_pk_add_f32 v[60:61], v[60:61], v[34:35] op_sel_hi:[1,0] neg_lo:[0,1] neg_hi:[0,1]
	v_pk_add_f32 v[76:77], v[76:77], v[34:35] op_sel_hi:[1,0] neg_lo:[0,1] neg_hi:[0,1]
	v_pk_add_f32 v[62:63], v[62:63], v[34:35] op_sel_hi:[1,0] neg_lo:[0,1] neg_hi:[0,1]
	v_pk_add_f32 v[78:79], v[78:79], v[34:35] op_sel_hi:[1,0] neg_lo:[0,1] neg_hi:[0,1]
	v_exp_f32_e64 v35, -v84
	v_add_f32_e32 v204, v205, v84
	v_pk_add_f32 v[64:65], v[64:65], v[34:35] op_sel_hi:[1,0] neg_lo:[0,1] neg_hi:[0,1]
	v_pk_add_f32 v[80:81], v[80:81], v[34:35] op_sel_hi:[1,0] neg_lo:[0,1] neg_hi:[0,1]
	v_cndmask_b32_e64 v36, v35, 1.0, s[10:11]
	v_xor_b32_e32 v34, 0x80000000, v204
	v_pk_mul_f32 v[16:17], v[16:17], v[36:37] op_sel_hi:[1,0]
	v_pk_mul_f32 v[14:15], v[14:15], v[36:37] op_sel_hi:[1,0]
	v_pk_mul_f32 v[12:13], v[12:13], v[36:37] op_sel_hi:[1,0]
	v_pk_mul_f32 v[10:11], v[10:11], v[36:37] op_sel_hi:[1,0]
	v_pk_mul_f32 v[8:9], v[8:9], v[36:37] op_sel_hi:[1,0]
	v_pk_mul_f32 v[6:7], v[6:7], v[36:37] op_sel_hi:[1,0]
	v_pk_mul_f32 v[4:5], v[4:5], v[36:37] op_sel_hi:[1,0]
	v_pk_mul_f32 v[2:3], v[2:3], v[36:37] op_sel_hi:[1,0]
	v_pk_mul_f32 v[32:33], v[32:33], v[36:37] op_sel_hi:[1,0]
	v_pk_mul_f32 v[30:31], v[30:31], v[36:37] op_sel_hi:[1,0]
	v_pk_mul_f32 v[28:29], v[28:29], v[36:37] op_sel_hi:[1,0]
	v_pk_mul_f32 v[26:27], v[26:27], v[36:37] op_sel_hi:[1,0]
	v_pk_mul_f32 v[24:25], v[24:25], v[36:37] op_sel_hi:[1,0]
	v_pk_mul_f32 v[22:23], v[22:23], v[36:37] op_sel_hi:[1,0]
	v_pk_mul_f32 v[20:21], v[20:21], v[36:37] op_sel_hi:[1,0]
	v_pk_mul_f32 v[18:19], v[18:19], v[36:37] op_sel_hi:[1,0]
	v_mul_f32_e32 v203, v203, v36
	v_mov_b32_e32 v35, v34
	v_mov_b32_e32 v36, v34
	v_mov_b32_e32 v37, v34
	v_mov_b32_e32 v38, v34
	v_mov_b32_e32 v39, v34
	v_mov_b32_e32 v40, v34
	v_mov_b32_e32 v41, v34
	v_mov_b32_e32 v42, v34
	v_mov_b32_e32 v43, v34
	v_mov_b32_e32 v44, v34
	v_mov_b32_e32 v45, v34
	v_mov_b32_e32 v46, v34
	v_mov_b32_e32 v47, v34
	v_mov_b32_e32 v48, v34
	v_mov_b32_e32 v49, v34
	s_branch .LBB0_813
.Lat1_resc_b:
	v_max_f32_e32 v34, v51, v51
	v_max_f32_e32 v35, 0, v34
	v_exp_f32_e64 v36, -v35
	v_mov_b32_e32 v34, v35
	v_add_f32_e32 v205, v204, v35
	v_pk_add_f32 v[82:83], v[82:83], v[34:35] op_sel_hi:[1,0] neg_lo:[0,1] neg_hi:[0,1]
	v_pk_add_f32 v[98:99], v[98:99], v[34:35] op_sel_hi:[1,0] neg_lo:[0,1] neg_hi:[0,1]
	v_pk_add_f32 v[84:85], v[84:85], v[34:35] op_sel_hi:[1,0] neg_lo:[0,1] neg_hi:[0,1]
	v_pk_add_f32 v[100:101], v[100:101], v[34:35] op_sel_hi:[1,0] neg_lo:[0,1] neg_hi:[0,1]
	v_pk_add_f32 v[86:87], v[86:87], v[34:35] op_sel_hi:[1,0] neg_lo:[0,1] neg_hi:[0,1]
	v_pk_add_f32 v[102:103], v[102:103], v[34:35] op_sel_hi:[1,0] neg_lo:[0,1] neg_hi:[0,1]
	v_pk_add_f32 v[88:89], v[88:89], v[34:35] op_sel_hi:[1,0] neg_lo:[0,1] neg_hi:[0,1]
	v_pk_add_f32 v[104:105], v[104:105], v[34:35] op_sel_hi:[1,0] neg_lo:[0,1] neg_hi:[0,1]
	v_pk_add_f32 v[90:91], v[90:91], v[34:35] op_sel_hi:[1,0] neg_lo:[0,1] neg_hi:[0,1]
	v_pk_add_f32 v[106:107], v[106:107], v[34:35] op_sel_hi:[1,0] neg_lo:[0,1] neg_hi:[0,1]
	v_pk_add_f32 v[92:93], v[92:93], v[34:35] op_sel_hi:[1,0] neg_lo:[0,1] neg_hi:[0,1]
	v_pk_add_f32 v[108:109], v[108:109], v[34:35] op_sel_hi:[1,0] neg_lo:[0,1] neg_hi:[0,1]
	v_pk_add_f32 v[94:95], v[94:95], v[34:35] op_sel_hi:[1,0] neg_lo:[0,1] neg_hi:[0,1]
	v_pk_add_f32 v[110:111], v[110:111], v[34:35] op_sel_hi:[1,0] neg_lo:[0,1] neg_hi:[0,1]
	v_pk_add_f32 v[96:97], v[96:97], v[34:35] op_sel_hi:[1,0] neg_lo:[0,1] neg_hi:[0,1]
	v_pk_add_f32 v[112:113], v[112:113], v[34:35] op_sel_hi:[1,0] neg_lo:[0,1] neg_hi:[0,1]
	v_xor_b32_e32 v34, 0x80000000, v205
	v_pk_mul_f32 v[16:17], v[16:17], v[36:37] op_sel_hi:[1,0]
	v_pk_mul_f32 v[14:15], v[14:15], v[36:37] op_sel_hi:[1,0]
	v_pk_mul_f32 v[12:13], v[12:13], v[36:37] op_sel_hi:[1,0]
	v_pk_mul_f32 v[10:11], v[10:11], v[36:37] op_sel_hi:[1,0]
	v_pk_mul_f32 v[8:9], v[8:9], v[36:37] op_sel_hi:[1,0]
	v_pk_mul_f32 v[6:7], v[6:7], v[36:37] op_sel_hi:[1,0]
	v_pk_mul_f32 v[4:5], v[4:5], v[36:37] op_sel_hi:[1,0]
	v_pk_mul_f32 v[2:3], v[2:3], v[36:37] op_sel_hi:[1,0]
	v_pk_mul_f32 v[32:33], v[32:33], v[36:37] op_sel_hi:[1,0]
	v_pk_mul_f32 v[30:31], v[30:31], v[36:37] op_sel_hi:[1,0]
	v_pk_mul_f32 v[28:29], v[28:29], v[36:37] op_sel_hi:[1,0]
	v_pk_mul_f32 v[26:27], v[26:27], v[36:37] op_sel_hi:[1,0]
	v_pk_mul_f32 v[24:25], v[24:25], v[36:37] op_sel_hi:[1,0]
	v_pk_mul_f32 v[22:23], v[22:23], v[36:37] op_sel_hi:[1,0]
	v_pk_mul_f32 v[20:21], v[20:21], v[36:37] op_sel_hi:[1,0]
	v_pk_mul_f32 v[18:19], v[18:19], v[36:37] op_sel_hi:[1,0]
	v_mul_f32_e32 v180, v180, v36
	v_mov_b32_e32 v35, v34
	v_mov_b32_e32 v36, v34
	v_mov_b32_e32 v37, v34
	v_mov_b32_e32 v38, v34
	v_mov_b32_e32 v39, v34
	v_mov_b32_e32 v40, v34
	v_mov_b32_e32 v41, v34
	v_mov_b32_e32 v42, v34
	v_mov_b32_e32 v43, v34
	v_mov_b32_e32 v44, v34
	v_mov_b32_e32 v45, v34
	v_mov_b32_e32 v46, v34
	v_mov_b32_e32 v47, v34
	v_mov_b32_e32 v48, v34
	v_mov_b32_e32 v49, v34
	s_branch .LBB0_820

.LBB0_804:
	s_or_b64 exec, exec, s[8:9]
	global_load_dwordx4 v[146:149], v160, s[56:57] offset:128
	v_max_f32_e32 v83, v50, v51
	v_max3_f32 v84, v52, v53, v67
	v_max3_f32 v83, v83, v66, v68
	v_max3_f32 v83, v83, v69, v54
	v_max3_f32 v84, v84, v56, v57
	v_max3_f32 v83, v83, v55, v70
	v_max3_f32 v84, v84, v72, v73
	v_max3_f32 v83, v83, v71, v58
	v_max3_f32 v84, v84, v60, v61
	v_max3_f32 v83, v83, v59, v74
	v_max3_f32 v84, v84, v76, v77
	v_max3_f32 v83, v83, v75, v62
	v_max3_f32 v84, v84, v64, v65
	v_max3_f32 v83, v83, v63, v78
	v_max3_f32 v84, v84, v80, v81
	v_max3_f32 v83, v83, v79, v84
	v_mov_b32_e32 v84, v83
	s_cmp_eq_u32 s12, 0
	s_nop 0
	v_permlane32_swap_b32_e32 v83, v84
	v_max_f32_e32 v83, v83, v84
	s_cbranch_scc1 .Lat1_first
	v_cmp_lt_f32_e32 vcc, s97, v83
	s_cbranch_vccnz .Lat1_resc
	v_mov_b32_e32 v204, v205

.LBB0_817:
	s_or_b64 exec, exec, s[8:9]
	global_load_dwordx4 v[146:149], v160, s[56:57] offset:256
	v_add_f32_e32 v50, v66, v50
	v_add_u32_e32 v150, 0x6000, v150
	v_add_u32_e32 v152, 0x6000, v152
	v_add_u32_e32 v160, 0x100, v160
	v_add_f32_e32 v51, v67, v51
	v_add_f32_e32 v52, v68, v52
	v_add_f32_e32 v50, v51, v50
	v_add_f32_e32 v53, v69, v53
	v_add_f32_e32 v50, v52, v50
	v_add_f32_e32 v54, v70, v54
	v_add_f32_e32 v50, v53, v50
	v_add_f32_e32 v55, v71, v55
	v_add_f32_e32 v50, v54, v50
	v_max_f32_e32 v51, v82, v83
	v_add_f32_e32 v56, v72, v56
	v_add_f32_e32 v50, v55, v50
	v_max3_f32 v52, v84, v85, v99
	v_max3_f32 v51, v51, v98, v100
	v_add_f32_e32 v57, v73, v57
	v_add_f32_e32 v50, v56, v50
	v_max3_f32 v51, v51, v101, v86
	v_max3_f32 v52, v52, v88, v89
	v_add_f32_e32 v58, v74, v58
	v_add_f32_e32 v50, v57, v50
	v_max3_f32 v51, v51, v87, v102
	v_max3_f32 v52, v52, v104, v105
	v_add_f32_e32 v59, v75, v59
	v_add_f32_e32 v50, v58, v50
	v_max3_f32 v51, v51, v103, v90
	v_max3_f32 v52, v52, v92, v93
	v_add_f32_e32 v60, v76, v60
	v_add_f32_e32 v50, v59, v50
	v_max3_f32 v51, v51, v91, v106
	v_max3_f32 v52, v52, v108, v109
	v_add_f32_e32 v61, v77, v61
	v_add_f32_e32 v50, v60, v50
	v_max3_f32 v51, v51, v107, v94
	v_max3_f32 v52, v52, v96, v97
	v_add_f32_e32 v62, v78, v62
	v_add_f32_e32 v50, v61, v50
	v_max3_f32 v51, v51, v95, v110
	v_max3_f32 v52, v52, v112, v113
	v_add_f32_e32 v63, v79, v63
	v_add_f32_e32 v50, v62, v50
	v_max3_f32 v51, v51, v111, v52
	v_add_f32_e32 v64, v80, v64
	v_add_f32_e32 v50, v63, v50
	v_mov_b32_e32 v52, v51
	v_add_f32_e32 v65, v81, v65
	v_add_f32_e32 v50, v64, v50
	v_permlane32_swap_b32_e32 v51, v52
	v_add_f32_e32 v50, v65, v50
	v_add_f32_e32 v180, v203, v50
	v_max_f32_e32 v51, v51, v52
	v_cmp_lt_f32_e32 vcc, s97, v51
	s_cbranch_vccnz .Lat1_resc_b
	v_mov_b32_e32 v205, v204

.Lat2_apply:
	v_exp_f32_e64 v48, -v97
	v_mov_b32_e32 v0, v97
	v_add_f32_e32 v209, v210, v97
	v_pk_add_f32 v[64:65], v[64:65], v[0:1] op_sel_hi:[1,0] neg_lo:[0,1] neg_hi:[0,1]
	v_pk_add_f32 v[80:81], v[80:81], v[0:1] op_sel_hi:[1,0] neg_lo:[0,1] neg_hi:[0,1]
	v_pk_add_f32 v[66:67], v[66:67], v[0:1] op_sel_hi:[1,0] neg_lo:[0,1] neg_hi:[0,1]
	v_pk_add_f32 v[82:83], v[82:83], v[0:1] op_sel_hi:[1,0] neg_lo:[0,1] neg_hi:[0,1]
	v_pk_add_f32 v[68:69], v[68:69], v[0:1] op_sel_hi:[1,0] neg_lo:[0,1] neg_hi:[0,1]
	v_pk_add_f32 v[84:85], v[84:85], v[0:1] op_sel_hi:[1,0] neg_lo:[0,1] neg_hi:[0,1]
	v_pk_add_f32 v[70:71], v[70:71], v[0:1] op_sel_hi:[1,0] neg_lo:[0,1] neg_hi:[0,1]
	v_pk_add_f32 v[86:87], v[86:87], v[0:1] op_sel_hi:[1,0] neg_lo:[0,1] neg_hi:[0,1]
	v_pk_add_f32 v[72:73], v[72:73], v[0:1] op_sel_hi:[1,0] neg_lo:[0,1] neg_hi:[0,1]
	v_pk_add_f32 v[88:89], v[88:89], v[0:1] op_sel_hi:[1,0] neg_lo:[0,1] neg_hi:[0,1]
	v_pk_add_f32 v[74:75], v[74:75], v[0:1] op_sel_hi:[1,0] neg_lo:[0,1] neg_hi:[0,1]
	v_pk_add_f32 v[90:91], v[90:91], v[0:1] op_sel_hi:[1,0] neg_lo:[0,1] neg_hi:[0,1]
	v_pk_add_f32 v[76:77], v[76:77], v[0:1] op_sel_hi:[1,0] neg_lo:[0,1] neg_hi:[0,1]
	v_pk_add_f32 v[92:93], v[92:93], v[0:1] op_sel_hi:[1,0] neg_lo:[0,1] neg_hi:[0,1]
	v_pk_add_f32 v[78:79], v[78:79], v[0:1] op_sel_hi:[1,0] neg_lo:[0,1] neg_hi:[0,1]
	v_pk_add_f32 v[94:95], v[94:95], v[0:1] op_sel_hi:[1,0] neg_lo:[0,1] neg_hi:[0,1]
	v_cndmask_b32_e64 v0, v48, 1.0, s[10:11]
	v_xor_b32_e32 v48, 0x80000000, v209
	v_pk_mul_f32 v[46:47], v[46:47], v[0:1] op_sel_hi:[1,0]
	v_pk_mul_f32 v[44:45], v[44:45], v[0:1] op_sel_hi:[1,0]
	v_pk_mul_f32 v[42:43], v[42:43], v[0:1] op_sel_hi:[1,0]
	v_pk_mul_f32 v[40:41], v[40:41], v[0:1] op_sel_hi:[1,0]
	v_pk_mul_f32 v[38:39], v[38:39], v[0:1] op_sel_hi:[1,0]
	v_pk_mul_f32 v[36:37], v[36:37], v[0:1] op_sel_hi:[1,0]
	v_pk_mul_f32 v[34:35], v[34:35], v[0:1] op_sel_hi:[1,0]
	v_pk_mul_f32 v[32:33], v[32:33], v[0:1] op_sel_hi:[1,0]
	v_pk_mul_f32 v[30:31], v[30:31], v[0:1] op_sel_hi:[1,0]
	v_pk_mul_f32 v[28:29], v[28:29], v[0:1] op_sel_hi:[1,0]
	v_pk_mul_f32 v[26:27], v[26:27], v[0:1] op_sel_hi:[1,0]
	v_pk_mul_f32 v[24:25], v[24:25], v[0:1] op_sel_hi:[1,0]
	v_pk_mul_f32 v[22:23], v[22:23], v[0:1] op_sel_hi:[1,0]
	v_pk_mul_f32 v[20:21], v[20:21], v[0:1] op_sel_hi:[1,0]
	v_pk_mul_f32 v[18:19], v[18:19], v[0:1] op_sel_hi:[1,0]
	v_pk_mul_f32 v[16:17], v[16:17], v[0:1] op_sel_hi:[1,0]
	v_mul_f32_e32 v208, v208, v0
	v_mov_b32_e32 v49, v48
	v_mov_b32_e32 v50, v48
	v_mov_b32_e32 v51, v48
	v_mov_b32_e32 v52, v48
	v_mov_b32_e32 v53, v48
	v_mov_b32_e32 v54, v48
	v_mov_b32_e32 v55, v48
	v_mov_b32_e32 v56, v48
	v_mov_b32_e32 v57, v48
	v_mov_b32_e32 v58, v48
	v_mov_b32_e32 v59, v48
	v_mov_b32_e32 v60, v48
	v_mov_b32_e32 v61, v48
	v_mov_b32_e32 v62, v48
	v_mov_b32_e32 v63, v48
	s_branch .LBB0_889
.Lat2_resc_b:
	v_max_f32_e32 v3, v3, v3
	v_max_f32_e32 v3, 0, v3
	v_exp_f32_e64 v4, -v3
	v_add_f32_e32 v210, v209, v3
	v_mov_b32_e32 v2, v3
	v_xor_b32_e32 v48, 0x80000000, v210
	v_pk_add_f32 v[96:97], v[96:97], v[2:3] op_sel_hi:[1,0] neg_lo:[0,1] neg_hi:[0,1]
	v_pk_add_f32 v[112:113], v[112:113], v[2:3] op_sel_hi:[1,0] neg_lo:[0,1] neg_hi:[0,1]
	v_pk_add_f32 v[98:99], v[98:99], v[2:3] op_sel_hi:[1,0] neg_lo:[0,1] neg_hi:[0,1]
	v_pk_add_f32 v[114:115], v[114:115], v[2:3] op_sel_hi:[1,0] neg_lo:[0,1] neg_hi:[0,1]
	v_pk_add_f32 v[100:101], v[100:101], v[2:3] op_sel_hi:[1,0] neg_lo:[0,1] neg_hi:[0,1]
	v_pk_add_f32 v[116:117], v[116:117], v[2:3] op_sel_hi:[1,0] neg_lo:[0,1] neg_hi:[0,1]
	v_pk_add_f32 v[102:103], v[102:103], v[2:3] op_sel_hi:[1,0] neg_lo:[0,1] neg_hi:[0,1]
	v_pk_add_f32 v[118:119], v[118:119], v[2:3] op_sel_hi:[1,0] neg_lo:[0,1] neg_hi:[0,1]
	v_pk_add_f32 v[104:105], v[104:105], v[2:3] op_sel_hi:[1,0] neg_lo:[0,1] neg_hi:[0,1]
	v_pk_add_f32 v[120:121], v[120:121], v[2:3] op_sel_hi:[1,0] neg_lo:[0,1] neg_hi:[0,1]
	v_pk_add_f32 v[106:107], v[106:107], v[2:3] op_sel_hi:[1,0] neg_lo:[0,1] neg_hi:[0,1]
	v_pk_add_f32 v[122:123], v[122:123], v[2:3] op_sel_hi:[1,0] neg_lo:[0,1] neg_hi:[0,1]
	v_pk_add_f32 v[108:109], v[108:109], v[2:3] op_sel_hi:[1,0] neg_lo:[0,1] neg_hi:[0,1]
	v_pk_add_f32 v[124:125], v[124:125], v[2:3] op_sel_hi:[1,0] neg_lo:[0,1] neg_hi:[0,1]
	v_pk_add_f32 v[110:111], v[110:111], v[2:3] op_sel_hi:[1,0] neg_lo:[0,1] neg_hi:[0,1]
	v_pk_add_f32 v[126:127], v[126:127], v[2:3] op_sel_hi:[1,0] neg_lo:[0,1] neg_hi:[0,1]
	v_pk_mul_f32 v[46:47], v[46:47], v[4:5] op_sel_hi:[1,0]
	v_pk_mul_f32 v[44:45], v[44:45], v[4:5] op_sel_hi:[1,0]
	v_pk_mul_f32 v[42:43], v[42:43], v[4:5] op_sel_hi:[1,0]
	v_pk_mul_f32 v[40:41], v[40:41], v[4:5] op_sel_hi:[1,0]
	v_pk_mul_f32 v[38:39], v[38:39], v[4:5] op_sel_hi:[1,0]
	v_pk_mul_f32 v[36:37], v[36:37], v[4:5] op_sel_hi:[1,0]
	v_pk_mul_f32 v[34:35], v[34:35], v[4:5] op_sel_hi:[1,0]
	v_pk_mul_f32 v[32:33], v[32:33], v[4:5] op_sel_hi:[1,0]
	v_pk_mul_f32 v[30:31], v[30:31], v[4:5] op_sel_hi:[1,0]
	v_pk_mul_f32 v[28:29], v[28:29], v[4:5] op_sel_hi:[1,0]
	v_pk_mul_f32 v[26:27], v[26:27], v[4:5] op_sel_hi:[1,0]
	v_pk_mul_f32 v[24:25], v[24:25], v[4:5] op_sel_hi:[1,0]
	v_pk_mul_f32 v[22:23], v[22:23], v[4:5] op_sel_hi:[1,0]
	v_pk_mul_f32 v[20:21], v[20:21], v[4:5] op_sel_hi:[1,0]
	v_pk_mul_f32 v[18:19], v[18:19], v[4:5] op_sel_hi:[1,0]
	v_pk_mul_f32 v[16:17], v[16:17], v[4:5] op_sel_hi:[1,0]
	v_mul_f32_e32 v188, v188, v4
	v_mov_b32_e32 v49, v48
	v_mov_b32_e32 v50, v48
	v_mov_b32_e32 v51, v48
	v_mov_b32_e32 v52, v48
	v_mov_b32_e32 v53, v48
	v_mov_b32_e32 v54, v48
	v_mov_b32_e32 v55, v48
	v_mov_b32_e32 v56, v48
	v_mov_b32_e32 v57, v48
	v_mov_b32_e32 v58, v48
	v_mov_b32_e32 v59, v48
	v_mov_b32_e32 v60, v48
	v_mov_b32_e32 v61, v48
	v_mov_b32_e32 v62, v48
	v_mov_b32_e32 v63, v48
	s_branch .LBB0_875
.LBB0_873:
	s_or_b64 exec, exec, s[8:9]
	global_load_dwordx4 v[160:163], v182, s[56:57] offset:256
	v_add_f32_e32 v4, v82, v66
	v_add_u32_e32 v178, 0x6000, v178
	v_add_u32_e32 v180, 0x6000, v180
	v_add_u32_e32 v182, 0x100, v182
	v_add_f32_e32 v2, v80, v64
	v_add_f32_e32 v3, v81, v65
	v_add_f32_e32 v2, v3, v2
	v_add_f32_e32 v5, v83, v67
	v_add_f32_e32 v2, v4, v2
	v_add_f32_e32 v6, v84, v68
	v_add_f32_e32 v2, v5, v2
	v_add_f32_e32 v7, v85, v69
	v_add_f32_e32 v2, v6, v2
	v_max_f32_e32 v3, v96, v97
	v_add_f32_e32 v8, v86, v70
	v_add_f32_e32 v2, v7, v2
	v_max3_f32 v4, v98, v99, v113
	v_max3_f32 v3, v3, v112, v114
	v_add_f32_e32 v9, v87, v71
	v_add_f32_e32 v2, v8, v2
	v_max3_f32 v3, v3, v115, v100
	v_max3_f32 v4, v4, v102, v103
	v_add_f32_e32 v10, v88, v72
	v_add_f32_e32 v2, v9, v2
	v_max3_f32 v3, v3, v101, v116
	v_max3_f32 v4, v4, v118, v119
	v_add_f32_e32 v11, v89, v73
	v_add_f32_e32 v2, v10, v2
	v_max3_f32 v3, v3, v117, v104
	v_max3_f32 v4, v4, v106, v107
	v_add_f32_e32 v12, v90, v74
	v_add_f32_e32 v2, v11, v2
	v_max3_f32 v3, v3, v105, v120
	v_max3_f32 v4, v4, v122, v123
	v_add_f32_e32 v13, v91, v75
	v_add_f32_e32 v2, v12, v2
	v_max3_f32 v3, v3, v121, v108
	v_max3_f32 v4, v4, v110, v111
	v_add_f32_e32 v14, v92, v76
	v_add_f32_e32 v2, v13, v2
	v_max3_f32 v3, v3, v109, v124
	v_max3_f32 v4, v4, v126, v127
	v_add_f32_e32 v15, v93, v77
	v_add_f32_e32 v2, v14, v2
	v_max3_f32 v3, v3, v125, v4
	v_add_f32_e32 v64, v94, v78
	v_add_f32_e32 v2, v15, v2
	v_mov_b32_e32 v4, v3
	v_add_f32_e32 v65, v95, v79
	v_add_f32_e32 v2, v64, v2
	v_permlane32_swap_b32_e32 v3, v4
	v_add_f32_e32 v2, v65, v2
	v_add_f32_e32 v188, v208, v2
	v_max_f32_e32 v3, v3, v4
	v_cmp_lt_f32_e32 vcc, s97, v3
	s_cbranch_vccnz .Lat2_resc_b
	v_mov_b32_e32 v210, v209

.LBB0_880:
	s_or_b64 exec, exec, s[8:9]
	global_load_dwordx4 v[6:9], v182, s[56:57] offset:128
	v_max_f32_e32 v96, v64, v65
	v_max3_f32 v97, v66, v67, v81
	v_max3_f32 v96, v96, v80, v82
	v_max3_f32 v96, v96, v83, v68
	v_max3_f32 v97, v97, v70, v71
	v_max3_f32 v96, v96, v69, v84
	v_max3_f32 v97, v97, v86, v87
	v_max3_f32 v96, v96, v85, v72
	v_max3_f32 v97, v97, v74, v75
	v_max3_f32 v96, v96, v73, v88
	v_max3_f32 v97, v97, v90, v91
	v_max3_f32 v96, v96, v89, v76
	v_max3_f32 v97, v97, v78, v79
	v_max3_f32 v96, v96, v77, v92
	v_max3_f32 v97, v97, v94, v95
	v_max3_f32 v96, v96, v93, v97
	v_mov_b32_e32 v97, v96
	s_cmp_eq_u32 s76, 0
	s_nop 0
	v_permlane32_swap_b32_e32 v96, v97
	v_max_f32_e32 v96, v96, v97
	s_cbranch_scc1 .Lat2_first
	v_cmp_lt_f32_e32 vcc, s97, v96
	s_cbranch_vccnz .Lat2_resc
	v_mov_b32_e32 v209, v210
